# attention tile loop: graded s_setprio 3/2/1/0 across QK first/second half and PV first/second half (the wave that is behind always outranks its partner)
# speedup vs baseline: 1.0042x; 1.0042x over previous
; #define SBAR() __builtin_amdgcn_sched_barrier(0)
; __device__ __forceinline__ void finishSM(f32x16& p0, f32x16& p1, float alpha, float& l_reg, bf16x8& pa0, bf16x8& pa1, bf16x8& pa2, bf16x8& pa3) {
; #pragma unroll
;     for (int r = 0; r < 16; ++r) p1[r] = __builtin_amdgcn_exp2f(p1[r]);
;     float ps = 0;
; #pragma unroll
;     for (int r = 0; r < 16; ++r) ps += p0[r];
; #pragma unroll
;     for (int r = 0; r < 16; ++r) ps += p1[r];
;     { auto rr = __builtin_amdgcn_permlane32_swap(__float_as_uint(ps), __float_as_uint(ps), false, false);
;       ps = __uint_as_float(rr[0]) + __uint_as_float(rr[1]); }
;     l_reg = l_reg * alpha + ps;
;     ...
;     PK4(p0, 0, pa0); PK4(p0, 8, pa1); PK4(p1, 0, pa2); PK4(p1, 8, pa3);
;     ...
; }
; __device__ __forceinline__ void qkt(f32x16& p0, f32x16& p1, const char* Kn, const bf16x8* qr, int r32, int hi) {
;     const char* Kr = Kn + KR_OFF;
;     p0 = f32x16{}; p1 = f32x16{};
;     __builtin_amdgcn_s_setprio(1);
; #pragma unroll
;     for (int d0 = 0; d0 < 8; ++d0) { const int cb = (d0 * 16 + hi * 8) * 2;
;         const bf16x8 b0 = *reinterpret_cast<const bf16x8*>(Kn + KNSWZ(r32, cb));
;         const bf16x8 b1 = *reinterpret_cast<const bf16x8*>(Kn + KNSWZ(32 + r32, cb));
;         p0 = __builtin_amdgcn_mfma_f32_32x32x16_bf16(b0, qr[d0], p0, 0, 0, 0);
;         p1 = __builtin_amdgcn_mfma_f32_32x32x16_bf16(b1, qr[d0], p1, 0, 0, 0); }
; #pragma unroll
;     for (int d0 = 0; d0 < 4; ++d0) { const int cb = (d0 * 16 + hi * 8) * 2;
;         const bf16x8 b0 = *reinterpret_cast<const bf16x8*>(Kr + KRSWZ(r32, cb));
;         const bf16x8 b1 = *reinterpret_cast<const bf16x8*>(Kr + KRSWZ(32 + r32, cb));
;         p0 = __builtin_amdgcn_mfma_f32_32x32x16_bf16(b0, qr[8 + d0], p0, 0, 0, 0);
;         p1 = __builtin_amdgcn_mfma_f32_32x32x16_bf16(b1, qr[8 + d0], p1, 0, 0, 0); }
; }
; template <int D0> __device__ __forceinline__ void pv_one(f32x16& od, int vb, bf16x8 pa0, bf16x8 pa1, bf16x8 pa2, bf16x8 pa3) {
;     const s16x4 l0 = tr_read<v_rd_off(D0, 0, 0)>(vb), h0 = tr_read<v_rd_off(D0, 0, 1)>(vb), l1 = tr_read<v_rd_off(D0, 1, 0)>(vb), h1 = tr_read<v_rd_off(D0, 1, 1)>(vb);
;     const s16x4 l2 = tr_read<v_rd_off(D0, 2, 0)>(vb), h2 = tr_read<v_rd_off(D0, 2, 1)>(vb), l3 = tr_read<v_rd_off(D0, 3, 0)>(vb), h3 = tr_read<v_rd_off(D0, 3, 1)>(vb);
;     asm volatile("s_waitcnt lgkmcnt(0)" ::: "memory"); SBAR();
.LBB0_216:
	s_mul_i32 s0, s9, 0x6000
	s_add_i32 s14, s0, 0
	s_lshl_b32 s13, s9, 14
	s_add_i32 s16, s14, s6
	s_add_i32 s17, s7, s13
	s_add_i32 s18, s14, s8
	s_mov_b32 s13, s10
	s_mov_b32 s10, s15
	s_mul_i32 s0, s13, 0x6000
	s_add_i32 s0, s0, 0
	s_setprio 3
	v_add_u32_e32 v84, s0, v207
	ds_read_b128 v[80:83], v84
	ds_read_b128 v[84:87], v84 offset:8192
	v_add_u32_e32 v168, s0, v210
	ds_read_b128 v[196:199], v168
	ds_read_b128 v[168:171], v168 offset:8192
	v_add_u32_e32 v184, s0, v218
	s_waitcnt lgkmcnt(0)
	v_mfma_f32_32x32x16_bf16 v[96:111], v[80:83], v[156:159], 0
	v_mfma_f32_32x32x16_bf16 v[80:95], v[84:87], v[156:159], 0
	v_mfma_f32_32x32x16_bf16 v[96:111], v[196:199], v[152:155], v[96:111]
	v_mfma_f32_32x32x16_bf16 v[80:95], v[168:171], v[152:155], v[80:95]
	ds_read_b128 v[168:171], v184
	ds_read_b128 v[196:199], v184 offset:8192
	v_add_u32_e32 v184, s0, v221
	s_mov_b32 m0, s16
	s_add_u32 s100, s72, 0x26500000
	s_addc_u32 s101, s73, 0
	global_load_lds_dwordx4 v178, s[100:101]
	s_waitcnt lgkmcnt(0)
	v_mfma_f32_32x32x16_bf16 v[96:111], v[168:171], v[148:151], v[96:111]
	v_mfma_f32_32x32x16_bf16 v[80:95], v[196:199], v[148:151], v[80:95]
	ds_read_b128 v[168:171], v184
	ds_read_b128 v[196:199], v184 offset:8192
	v_add_u32_e32 v184, s0, v222
	s_waitcnt lgkmcnt(0)
	v_mfma_f32_32x32x16_bf16 v[96:111], v[168:171], v[144:147], v[96:111]
	v_mfma_f32_32x32x16_bf16 v[80:95], v[196:199], v[144:147], v[80:95]
	ds_read_b128 v[168:171], v184
	ds_read_b128 v[196:199], v184 offset:8192
	v_add_u32_e32 v184, s0, v223
	s_add_i32 m0, s16, 0x400
	s_nop 0
	global_load_lds_dwordx4 v180, s[100:101]
	s_waitcnt lgkmcnt(0)
	v_mfma_f32_32x32x16_bf16 v[96:111], v[168:171], v[140:143], v[96:111]
	v_mfma_f32_32x32x16_bf16 v[80:95], v[196:199], v[140:143], v[80:95]
	ds_read_b128 v[168:171], v184
	ds_read_b128 v[196:199], v184 offset:8192
	v_add_u32_e32 v184, s0, v224
	v_exp_f32_e32 v233, v73
	s_waitcnt lgkmcnt(0)
	v_mfma_f32_32x32x16_bf16 v[96:111], v[168:171], v[136:139], v[96:111]
	v_mfma_f32_32x32x16_bf16 v[80:95], v[196:199], v[136:139], v[80:95]
	ds_read_b128 v[168:171], v184
	ds_read_b128 v[196:199], v184 offset:8192
	v_add_u32_e32 v184, s0, v225
	s_mov_b32 m0, s17
	s_add_u32 s100, s72, 0x26500100
	s_addc_u32 s101, s73, 0
	global_load_lds_dwordx4 v176, s[100:101]
	v_exp_f32_e32 v250, v74
	s_setprio 2
	s_waitcnt lgkmcnt(0)
	v_mfma_f32_32x32x16_bf16 v[96:111], v[168:171], v[132:135], v[96:111]
	v_mfma_f32_32x32x16_bf16 v[80:95], v[196:199], v[132:135], v[80:95]
	ds_read_b128 v[168:171], v184
	ds_read_b128 v[196:199], v184 offset:8192
	v_add_u32_e32 v184, s0, v226
	v_exp_f32_e32 v200, v75
	s_waitcnt lgkmcnt(0)
	v_mfma_f32_32x32x16_bf16 v[96:111], v[168:171], v[128:131], v[96:111]
	v_mfma_f32_32x32x16_bf16 v[80:95], v[196:199], v[128:131], v[80:95]
	ds_read_b128 v[168:171], v184 offset:16384
	ds_read_b128 v[196:199], v184 offset:20480
	v_add_u32_e32 v184, s0, v227
	s_add_i32 m0, s17, 0x400
	s_add_u32 s100, s72, 0x26500180
	s_addc_u32 s101, s73, 0
	global_load_lds_dwordx4 v176, s[100:101]
	v_exp_f32_e32 v195, v76
	s_waitcnt lgkmcnt(0)
	v_mfma_f32_32x32x16_bf16 v[96:111], v[168:171], v[124:127], v[96:111]
	v_mfma_f32_32x32x16_bf16 v[80:95], v[196:199], v[124:127], v[80:95]
	ds_read_b128 v[168:171], v184 offset:16384
	ds_read_b128 v[196:199], v184 offset:20480
	v_add_u32_e32 v184, s0, v228
	v_exp_f32_e32 v172, v77
	s_waitcnt lgkmcnt(0)
	v_mfma_f32_32x32x16_bf16 v[96:111], v[168:171], v[120:123], v[96:111]
	v_mfma_f32_32x32x16_bf16 v[80:95], v[196:199], v[120:123], v[80:95]
	ds_read_b128 v[168:171], v184 offset:16384
	ds_read_b128 v[196:199], v184 offset:20480
	v_add_u32_e32 v184, s0, v229
	s_add_i32 m0, s18, 0x4000
	s_add_u32 s100, s72, 0x21204000
	s_addc_u32 s101, s73, 0
	global_load_lds_dwordx4 v174, s[100:101]
	v_exp_f32_e32 v173, v78
	s_waitcnt lgkmcnt(0)
	v_mfma_f32_32x32x16_bf16 v[96:111], v[168:171], v[116:119], v[96:111]
	v_mfma_f32_32x32x16_bf16 v[80:95], v[196:199], v[116:119], v[80:95]
	ds_read_b128 v[168:171], v184 offset:16384
	ds_read_b128 v[196:199], v184 offset:20480
	v_exp_f32_e32 v184, v68
	v_exp_f32_e32 v79, v79
	s_waitcnt lgkmcnt(0)
	v_mfma_f32_32x32x16_bf16 v[96:111], v[168:171], v[112:115], v[96:111]
	v_exp_f32_e32 v168, v64
	v_add_f32_e32 v64, 0, v247
	v_add_f32_e32 v64, v249, v64
	v_add_f32_e32 v64, v245, v64
	v_add_f32_e32 v64, v248, v64
	v_add_f32_e32 v64, v244, v64
	v_add_f32_e32 v64, v246, v64
	v_add_f32_e32 v64, v242, v64
	v_add_f32_e32 v64, v243, v64
	v_add_f32_e32 v64, v239, v64
	v_add_f32_e32 v64, v241, v64
	v_add_f32_e32 v64, v238, v64
	v_add_f32_e32 v64, v240, v64
	v_add_f32_e32 v64, v235, v64
	v_exp_f32_e32 v169, v65
	v_add_f32_e32 v64, v237, v64
	v_exp_f32_e32 v170, v66
	v_add_f32_e32 v64, v234, v64
	v_exp_f32_e32 v171, v67
	v_add_f32_e32 v64, v236, v64
	v_add_f32_e32 v64, v168, v64
	v_mfma_f32_32x32x16_bf16 v[80:95], v[196:199], v[112:115], v[80:95]
	v_exp_f32_e32 v196, v69
	v_add_f32_e32 v64, v169, v64
	v_exp_f32_e32 v197, v70
	v_add_f32_e32 v64, v170, v64
	v_exp_f32_e32 v198, v71
	v_add_f32_e32 v64, v171, v64
	v_exp_f32_e32 v199, v72
	v_add_f32_e32 v64, v184, v64
	v_add_f32_e32 v64, v196, v64
	v_add_f32_e32 v64, v197, v64
	v_add_f32_e32 v64, v198, v64
	v_add_f32_e32 v64, v199, v64
	v_add_f32_e32 v64, v233, v64
	v_add_f32_e32 v64, v250, v64
	v_add_f32_e32 v64, v200, v64
	v_add_f32_e32 v64, v195, v64
	v_add_f32_e32 v64, v172, v64
	v_add_f32_e32 v64, v173, v64
	v_add_f32_e32 v231, v79, v64
	v_mov_b32_e32 v232, v231
	v_cvt_pk_bf16_f32 v64, v247, v249
	v_cvt_pk_bf16_f32 v65, v245, v248
	v_cvt_pk_bf16_f32 v66, v244, v246
	s_nop 1
	v_permlane32_swap_b32_e32 v231, v232
	v_cvt_pk_bf16_f32 v67, v242, v243
	v_permlane32_swap_b32_e32 v64, v66
	v_cvt_pk_bf16_f32 v68, v239, v241
	v_cvt_pk_bf16_f32 v69, v238, v240
	v_cvt_pk_bf16_f32 v70, v235, v237
	v_cvt_pk_bf16_f32 v71, v234, v236
	v_cvt_pk_bf16_f32 v72, v168, v169
	v_cvt_pk_bf16_f32 v73, v170, v171
	v_cvt_pk_bf16_f32 v74, v184, v196
	v_cvt_pk_bf16_f32 v75, v197, v198
	v_cvt_pk_bf16_f32 v76, v199, v233
	v_cvt_pk_bf16_f32 v77, v250, v200
	v_cvt_pk_bf16_f32 v78, v195, v172
	v_cvt_pk_bf16_f32 v79, v173, v79
	s_lshl_b32 s15, s15, 14
	v_add_u32_e32 v172, s15, v205
	ds_read_b64_tr_b16 v[168:169], v172 offset:0
	ds_read_b64_tr_b16 v[170:171], v172 offset:0x800
	ds_read_b64_tr_b16 v[196:197], v172 offset:0x1000
	ds_read_b64_tr_b16 v[198:199], v172 offset:0x1800
	ds_read_b64_tr_b16 v[234:235], v172 offset:0x2000
	ds_read_b64_tr_b16 v[236:237], v172 offset:0x2800
	ds_read_b64_tr_b16 v[238:239], v172 offset:0x3000
	ds_read_b64_tr_b16 v[240:241], v172 offset:0x3800
	v_permlane32_swap_b32_e32 v65, v67
	v_permlane32_swap_b32_e32 v68, v70
	v_permlane32_swap_b32_e32 v69, v71
	v_permlane32_swap_b32_e32 v72, v74
	v_permlane32_swap_b32_e32 v73, v75
	v_permlane32_swap_b32_e32 v76, v78
	v_permlane32_swap_b32_e32 v77, v79
	s_setprio 1
	s_waitcnt lgkmcnt(0)
; #define SBAR() __builtin_amdgcn_sched_barrier(0)
; __device__ __forceinline__ void qkt(f32x16& p0, f32x16& p1, const char* Kn, const bf16x8* qr, int r32, int hi) {
;     const char* Kr = Kn + KR_OFF;
;     p0 = f32x16{}; p1 = f32x16{};
;     __builtin_amdgcn_s_setprio(1);
; #pragma unroll
;     for (int d0 = 0; d0 < 8; ++d0) { const int cb = (d0 * 16 + hi * 8) * 2;
;         const bf16x8 b0 = *reinterpret_cast<const bf16x8*>(Kn + KNSWZ(r32, cb));
;         const bf16x8 b1 = *reinterpret_cast<const bf16x8*>(Kn + KNSWZ(32 + r32, cb));
;         p0 = __builtin_amdgcn_mfma_f32_32x32x16_bf16(b0, qr[d0], p0, 0, 0, 0);
;         p1 = __builtin_amdgcn_mfma_f32_32x32x16_bf16(b1, qr[d0], p1, 0, 0, 0); }
; #pragma unroll
;     for (int d0 = 0; d0 < 4; ++d0) { const int cb = (d0 * 16 + hi * 8) * 2;
;         const bf16x8 b0 = *reinterpret_cast<const bf16x8*>(Kr + KRSWZ(r32, cb));
;         const bf16x8 b1 = *reinterpret_cast<const bf16x8*>(Kr + KRSWZ(32 + r32, cb));
;         p0 = __builtin_amdgcn_mfma_f32_32x32x16_bf16(b0, qr[8 + d0], p0, 0, 0, 0);
;         p1 = __builtin_amdgcn_mfma_f32_32x32x16_bf16(b1, qr[8 + d0], p1, 0, 0, 0); }
; }
; __device__ __forceinline__ int v_st(int k, int c) { const int kk = (k & ~0xC) | ((k & 4) << 1) | ((k & 8) >> 1); return ((kk >> 3) * 4 + (c >> 5)) * 512 + ((kk & 7) * 32 + (c & 31)) * 2; }
; __device__ __forceinline__ int v_rd_base(int lane) { return ((lane & 3) << 3) | (((lane >> 2) & 3) << 6) | (((lane >> 4) & 1) << 5) | (((lane >> 5) & 1) << 8); }
; template <int OFF> __device__ __forceinline__ s16x4 tr_read(int vb) {
;     s16x4 r; asm volatile("ds_read_b64_tr_b16 %0, %1 offset:%2" : "=&v"(r) : "v"(vb), "i"(OFF) : "memory"); return r;
; }
; template <int D0> __device__ __forceinline__ void pv_one(f32x16& od, int vb, bf16x8 pa0, bf16x8 pa1, bf16x8 pa2, bf16x8 pa3) {
;     const s16x4 l0 = tr_read<v_rd_off(D0, 0, 0)>(vb), h0 = tr_read<v_rd_off(D0, 0, 1)>(vb), l1 = tr_read<v_rd_off(D0, 1, 0)>(vb), h1 = tr_read<v_rd_off(D0, 1, 1)>(vb);
;     const s16x4 l2 = tr_read<v_rd_off(D0, 2, 0)>(vb), h2 = tr_read<v_rd_off(D0, 2, 1)>(vb), l3 = tr_read<v_rd_off(D0, 3, 0)>(vb), h3 = tr_read<v_rd_off(D0, 3, 1)>(vb);
;     asm volatile("s_waitcnt lgkmcnt(0)" ::: "memory"); SBAR();
;     ...
;     od = __builtin_amdgcn_mfma_f32_32x32x16_bf16(pa0, PK(l0, h0), od, 0, 0, 0);
;     od = __builtin_amdgcn_mfma_f32_32x32x16_bf16(pa1, PK(l1, h1), od, 0, 0, 0);
	s_nop 0
	v_mfma_f32_32x32x16_bf16 v[0:15], v[64:67], v[168:171], v[0:15]
	ds_read_b64_tr_b16 v[168:169], v172 offset:0x200
	ds_read_b64_tr_b16 v[170:171], v172 offset:0xa00
	v_mfma_f32_32x32x16_bf16 v[0:15], v[68:71], v[196:199], v[0:15]
	ds_read_b64_tr_b16 v[196:197], v172 offset:0x1200
	ds_read_b64_tr_b16 v[198:199], v172 offset:0x1a00
	v_mfma_f32_32x32x16_bf16 v[0:15], v[72:75], v[234:237], v[0:15]
	ds_read_b64_tr_b16 v[234:235], v172 offset:0x2200
	ds_read_b64_tr_b16 v[236:237], v172 offset:0x2a00
	v_mfma_f32_32x32x16_bf16 v[0:15], v[76:79], v[238:241], v[0:15]
	ds_read_b64_tr_b16 v[238:239], v172 offset:0x3200
	ds_read_b64_tr_b16 v[240:241], v172 offset:0x3a00
	s_waitcnt lgkmcnt(0)
	v_mfma_f32_32x32x16_bf16 v[48:63], v[64:67], v[168:171], v[48:63]
	ds_read_b64_tr_b16 v[168:169], v172 offset:0x400
	ds_read_b64_tr_b16 v[170:171], v172 offset:0xc00
	v_mfma_f32_32x32x16_bf16 v[48:63], v[68:71], v[196:199], v[48:63]
	ds_read_b64_tr_b16 v[196:197], v172 offset:0x1400
	ds_read_b64_tr_b16 v[198:199], v172 offset:0x1c00
	v_mfma_f32_32x32x16_bf16 v[48:63], v[72:75], v[234:237], v[48:63]
	ds_read_b64_tr_b16 v[234:235], v172 offset:0x2400
	ds_read_b64_tr_b16 v[236:237], v172 offset:0x2c00
	v_mfma_f32_32x32x16_bf16 v[48:63], v[76:79], v[238:241], v[48:63]
	ds_read_b64_tr_b16 v[238:239], v172 offset:0x3400
	ds_read_b64_tr_b16 v[240:241], v172 offset:0x3c00
	s_waitcnt lgkmcnt(0)
	s_setprio 0
	v_mfma_f32_32x32x16_bf16 v[32:47], v[64:67], v[168:171], v[32:47]
	ds_read_b64_tr_b16 v[168:169], v172 offset:0x600
	ds_read_b64_tr_b16 v[170:171], v172 offset:0xe00
	v_mfma_f32_32x32x16_bf16 v[32:47], v[68:71], v[196:199], v[32:47]
	ds_read_b64_tr_b16 v[196:197], v172 offset:0x1600
	ds_read_b64_tr_b16 v[198:199], v172 offset:0x1e00
	v_mfma_f32_32x32x16_bf16 v[32:47], v[72:75], v[234:237], v[32:47]
	ds_read_b64_tr_b16 v[234:235], v172 offset:0x2600
	ds_read_b64_tr_b16 v[236:237], v172 offset:0x2e00
	v_mfma_f32_32x32x16_bf16 v[32:47], v[76:79], v[238:241], v[32:47]
	ds_read_b64_tr_b16 v[238:239], v172 offset:0x3600
	ds_read_b64_tr_b16 v[240:241], v172 offset:0x3e00
	s_waitcnt lgkmcnt(0)
	v_mfma_f32_32x32x16_bf16 v[16:31], v[64:67], v[168:171], v[16:31]
	v_max_f32_e32 v64, v97, v97
	v_max_f32_e32 v65, v96, v96
	v_max_f32_e32 v64, v65, v64
	v_max3_f32 v64, v64, v98, v99
	v_max3_f32 v64, v64, v100, v101
	v_max3_f32 v64, v64, v102, v103
	v_max3_f32 v64, v64, v104, v105
	v_mfma_f32_32x32x16_bf16 v[16:31], v[68:71], v[196:199], v[16:31]
	v_max3_f32 v64, v64, v106, v107
	v_max3_f32 v64, v64, v108, v109
	v_max3_f32 v64, v64, v110, v111
	v_max3_f32 v64, v64, v80, v81
	v_max3_f32 v64, v64, v82, v83
	v_max3_f32 v64, v64, v84, v85
	v_max3_f32 v64, v64, v86, v87
	v_mfma_f32_32x32x16_bf16 v[16:31], v[72:75], v[234:237], v[16:31]
	v_max3_f32 v64, v64, v88, v89
	v_max3_f32 v64, v64, v90, v91
	v_max3_f32 v64, v64, v92, v93
	v_max3_f32 v64, v64, v94, v95
	v_mov_b32_e32 v65, v64
	s_nop 1
	v_permlane32_swap_b32_e32 v64, v65
	v_max_f32_e32 v65, v65, v65
	v_max_f32_e32 v64, v64, v64
	v_mfma_f32_32x32x16_bf16 v[16:31], v[76:79], v[238:241], v[16:31]
	v_max_f32_e32 v64, v64, v65
	v_sub_f32_e32 v65, v64, v182
	s_mov_b32 s0, 0x41300000
	v_cmp_ge_f32_e32 vcc, s0, v65
	v_mov_b32_e32 v184, v182
	v_mov_b32_e32 v233, 1.0
	s_cmp_eq_u64 vcc, exec
	s_cbranch_scc0 .Latt_slow1
	s_cmp_lg_u32 s19, 0
	s_cbranch_scc0 .LBB0_228
.LBB0_221:
	v_exp_f32_e32 v182, v98
	v_exp_f32_e32 v172, v96
	v_exp_f32_e32 v173, v97
	v_exp_f32_e32 v195, v99
	v_exp_f32_e32 v196, v100
	v_exp_f32_e32 v197, v101
	v_exp_f32_e32 v198, v102
	v_exp_f32_e32 v199, v103
	v_exp_f32_e32 v200, v104
	v_exp_f32_e32 v234, v105
	v_exp_f32_e32 v235, v106
	v_exp_f32_e32 v236, v107
	v_exp_f32_e32 v237, v108
	v_exp_f32_e32 v238, v109
	v_exp_f32_e32 v239, v110
	v_exp_f32_e32 v240, v111
	v_add_u32_e32 v68, s14, v207
	v_add_u32_e32 v186, s14, v210
	s_mul_i32 s0, s10, 0x6000
	s_add_i32 s16, s0, 0
	s_add_i32 s17, s16, s6
	s_add_i32 s18, s16, s8
	s_waitcnt vmcnt(0) lgkmcnt(0)
	s_barrier
	s_add_i32 s15, s7, s15
	s_setprio 3
	ds_read_b128 v[64:67], v68
	ds_read_b128 v[68:71], v68 offset:8192
	ds_read_b128 v[168:171], v186
	ds_read_b128 v[186:189], v186 offset:8192
	s_waitcnt lgkmcnt(0)
	v_mfma_f32_32x32x16_bf16 v[96:111], v[64:67], v[156:159], 0
	v_mfma_f32_32x32x16_bf16 v[64:79], v[68:71], v[156:159], 0
	v_mfma_f32_32x32x16_bf16 v[96:111], v[168:171], v[152:155], v[96:111]
	v_mfma_f32_32x32x16_bf16 v[64:79], v[186:189], v[152:155], v[64:79]
	v_add_u32_e32 v186, s14, v218
	ds_read_b128 v[168:171], v186
	ds_read_b128 v[186:189], v186 offset:8192
	s_mov_b32 m0, s17
	s_add_u32 s100, s72, 0x26580000
	s_addc_u32 s101, s73, 0
	global_load_lds_dwordx4 v178, s[100:101]
	s_waitcnt lgkmcnt(0)
	v_mfma_f32_32x32x16_bf16 v[96:111], v[168:171], v[148:151], v[96:111]
	v_mfma_f32_32x32x16_bf16 v[64:79], v[186:189], v[148:151], v[64:79]
	v_add_u32_e32 v186, s14, v221
	ds_read_b128 v[168:171], v186
	ds_read_b128 v[186:189], v186 offset:8192
	s_waitcnt lgkmcnt(0)
	v_mfma_f32_32x32x16_bf16 v[96:111], v[168:171], v[144:147], v[96:111]
	v_mfma_f32_32x32x16_bf16 v[64:79], v[186:189], v[144:147], v[64:79]
	v_add_u32_e32 v186, s14, v222
	ds_read_b128 v[168:171], v186
	ds_read_b128 v[186:189], v186 offset:8192
	s_add_i32 m0, s17, 0x400
	s_nop 0
	global_load_lds_dwordx4 v180, s[100:101]
	v_exp_f32_e32 v190, v88
	s_waitcnt lgkmcnt(0)
	v_mfma_f32_32x32x16_bf16 v[96:111], v[168:171], v[140:143], v[96:111]
	v_mfma_f32_32x32x16_bf16 v[64:79], v[186:189], v[140:143], v[64:79]
	v_add_u32_e32 v186, s14, v223
	ds_read_b128 v[168:171], v186
	ds_read_b128 v[186:189], v186 offset:8192
	v_exp_f32_e32 v191, v89
	s_waitcnt lgkmcnt(0)
; __device__ __forceinline__ void finishSM(f32x16& p0, f32x16& p1, float alpha, float& l_reg, bf16x8& pa0, bf16x8& pa1, bf16x8& pa2, bf16x8& pa3) {
; #pragma unroll
;     for (int r = 0; r < 16; ++r) p1[r] = __builtin_amdgcn_exp2f(p1[r]);
;     float ps = 0;
; #pragma unroll
;     for (int r = 0; r < 16; ++r) ps += p0[r];
; #pragma unroll
;     for (int r = 0; r < 16; ++r) ps += p1[r];
;     { auto rr = __builtin_amdgcn_permlane32_swap(__float_as_uint(ps), __float_as_uint(ps), false, false);
;       ps = __uint_as_float(rr[0]) + __uint_as_float(rr[1]); }
;     l_reg = l_reg * alpha + ps;
;     ...
;     PK4(p0, 0, pa0); PK4(p0, 8, pa1); PK4(p1, 0, pa2); PK4(p1, 8, pa3);
;     ...
; }
; __device__ __forceinline__ void qkt(f32x16& p0, f32x16& p1, const char* Kn, const bf16x8* qr, int r32, int hi) {
;     const char* Kr = Kn + KR_OFF;
;     p0 = f32x16{}; p1 = f32x16{};
;     __builtin_amdgcn_s_setprio(1);
; #pragma unroll
;     for (int d0 = 0; d0 < 8; ++d0) { const int cb = (d0 * 16 + hi * 8) * 2;
;         const bf16x8 b0 = *reinterpret_cast<const bf16x8*>(Kn + KNSWZ(r32, cb));
;         const bf16x8 b1 = *reinterpret_cast<const bf16x8*>(Kn + KNSWZ(32 + r32, cb));
;         p0 = __builtin_amdgcn_mfma_f32_32x32x16_bf16(b0, qr[d0], p0, 0, 0, 0);
;         p1 = __builtin_amdgcn_mfma_f32_32x32x16_bf16(b1, qr[d0], p1, 0, 0, 0); }
; #pragma unroll
;     for (int d0 = 0; d0 < 4; ++d0) { const int cb = (d0 * 16 + hi * 8) * 2;
;         const bf16x8 b0 = *reinterpret_cast<const bf16x8*>(Kr + KRSWZ(r32, cb));
;         const bf16x8 b1 = *reinterpret_cast<const bf16x8*>(Kr + KRSWZ(32 + r32, cb));
;         p0 = __builtin_amdgcn_mfma_f32_32x32x16_bf16(b0, qr[8 + d0], p0, 0, 0, 0);
;         p1 = __builtin_amdgcn_mfma_f32_32x32x16_bf16(b1, qr[8 + d0], p1, 0, 0, 0); }
; }
	v_mfma_f32_32x32x16_bf16 v[96:111], v[168:171], v[136:139], v[96:111]
	v_mfma_f32_32x32x16_bf16 v[64:79], v[186:189], v[136:139], v[64:79]
	v_add_u32_e32 v186, s14, v224
	ds_read_b128 v[168:171], v186
	ds_read_b128 v[186:189], v186 offset:8192
	s_mov_b32 m0, s15
	s_add_u32 s100, s72, 0x26580100
	s_addc_u32 s101, s73, 0
	global_load_lds_dwordx4 v176, s[100:101]
	v_exp_f32_e32 v192, v90
	s_setprio 2
	s_waitcnt lgkmcnt(0)
	v_mfma_f32_32x32x16_bf16 v[96:111], v[168:171], v[132:135], v[96:111]
	v_mfma_f32_32x32x16_bf16 v[64:79], v[186:189], v[132:135], v[64:79]
	v_add_u32_e32 v186, s14, v225
	ds_read_b128 v[168:171], v186
	ds_read_b128 v[186:189], v186 offset:8192
	v_exp_f32_e32 v193, v91
	s_waitcnt lgkmcnt(0)
	v_mfma_f32_32x32x16_bf16 v[96:111], v[168:171], v[128:131], v[96:111]
	v_mfma_f32_32x32x16_bf16 v[64:79], v[186:189], v[128:131], v[64:79]
	v_add_u32_e32 v186, s14, v226
	ds_read_b128 v[168:171], v186 offset:16384
	ds_read_b128 v[186:189], v186 offset:20480
	s_add_i32 m0, s15, 0x400
	s_add_u32 s100, s72, 0x26580180
	s_addc_u32 s101, s73, 0
	global_load_lds_dwordx4 v176, s[100:101]
	v_exp_f32_e32 v241, v92
	s_waitcnt lgkmcnt(0)
	v_mfma_f32_32x32x16_bf16 v[96:111], v[168:171], v[124:127], v[96:111]
	v_mfma_f32_32x32x16_bf16 v[64:79], v[186:189], v[124:127], v[64:79]
	v_add_u32_e32 v186, s14, v227
	ds_read_b128 v[168:171], v186 offset:16384
	ds_read_b128 v[186:189], v186 offset:20480
	v_exp_f32_e32 v242, v93
	s_waitcnt lgkmcnt(0)
	v_mfma_f32_32x32x16_bf16 v[96:111], v[168:171], v[120:123], v[96:111]
	v_mfma_f32_32x32x16_bf16 v[64:79], v[186:189], v[120:123], v[64:79]
	v_add_u32_e32 v186, s14, v228
	ds_read_b128 v[168:171], v186 offset:16384
	ds_read_b128 v[186:189], v186 offset:20480
	s_add_i32 m0, s18, 0x4000
	s_add_u32 s100, s72, 0x21206000
	s_addc_u32 s101, s73, 0
	global_load_lds_dwordx4 v174, s[100:101]
	v_exp_f32_e32 v94, v94
	s_waitcnt lgkmcnt(0)
	v_mfma_f32_32x32x16_bf16 v[96:111], v[168:171], v[116:119], v[96:111]
	v_mfma_f32_32x32x16_bf16 v[64:79], v[186:189], v[116:119], v[64:79]
	v_add_u32_e32 v186, s14, v229
	ds_read_b128 v[168:171], v186 offset:16384
	ds_read_b128 v[186:189], v186 offset:20480
	v_exp_f32_e32 v95, v95
	s_waitcnt lgkmcnt(0)
	v_mfma_f32_32x32x16_bf16 v[96:111], v[168:171], v[112:115], v[96:111]
	v_exp_f32_e32 v168, v80
	v_add_f32_e32 v80, 0, v172
	v_add_f32_e32 v80, v173, v80
	v_add_f32_e32 v80, v182, v80
	v_add_f32_e32 v80, v195, v80
	v_add_f32_e32 v80, v196, v80
	v_add_f32_e32 v80, v197, v80
	v_add_f32_e32 v80, v198, v80
	v_add_f32_e32 v80, v199, v80
	v_add_f32_e32 v80, v200, v80
	v_add_f32_e32 v80, v234, v80
	v_add_f32_e32 v80, v235, v80
	v_add_f32_e32 v80, v236, v80
	v_add_f32_e32 v80, v237, v80
	v_exp_f32_e32 v169, v81
	v_add_f32_e32 v80, v238, v80
	v_exp_f32_e32 v170, v82
	v_add_f32_e32 v80, v239, v80
	v_exp_f32_e32 v171, v83
	v_add_f32_e32 v80, v240, v80
	v_mfma_f32_32x32x16_bf16 v[64:79], v[186:189], v[112:115], v[64:79]
	v_exp_f32_e32 v186, v84
	v_add_f32_e32 v80, v168, v80
	v_exp_f32_e32 v187, v85
	v_add_f32_e32 v80, v169, v80
	v_exp_f32_e32 v188, v86
	v_add_f32_e32 v80, v170, v80
	v_exp_f32_e32 v189, v87
	v_add_f32_e32 v80, v171, v80
	v_add_f32_e32 v80, v186, v80
	v_add_f32_e32 v80, v187, v80
	v_add_f32_e32 v80, v188, v80
	v_add_f32_e32 v80, v189, v80
	v_add_f32_e32 v80, v190, v80
	v_add_f32_e32 v80, v191, v80
	v_add_f32_e32 v80, v192, v80
	v_add_f32_e32 v80, v193, v80
	v_add_f32_e32 v80, v241, v80
	v_add_f32_e32 v80, v242, v80
	v_add_f32_e32 v80, v94, v80
	v_add_f32_e32 v80, v95, v80
	v_mov_b32_e32 v81, v80
	v_cvt_pk_bf16_f32 v82, v172, v173
	v_cvt_pk_bf16_f32 v83, v182, v195
	v_cvt_pk_bf16_f32 v84, v196, v197
	s_nop 1
	v_permlane32_swap_b32_e32 v80, v81
	v_cvt_pk_bf16_f32 v85, v198, v199
	v_permlane32_swap_b32_e32 v82, v84
	v_cvt_pk_bf16_f32 v86, v200, v234
	v_cvt_pk_bf16_f32 v87, v235, v236
	v_cvt_pk_bf16_f32 v88, v237, v238
	v_cvt_pk_bf16_f32 v89, v239, v240
	v_cvt_pk_bf16_f32 v90, v168, v169
	v_cvt_pk_bf16_f32 v91, v170, v171
	v_cvt_pk_bf16_f32 v92, v186, v187
	v_cvt_pk_bf16_f32 v93, v188, v189
	v_cvt_pk_bf16_f32 v168, v190, v191
	v_cvt_pk_bf16_f32 v169, v192, v193
	v_cvt_pk_bf16_f32 v170, v241, v242
	v_cvt_pk_bf16_f32 v171, v94, v95
	v_lshl_add_u32 v94, s13, 14, v205
	ds_read_b64_tr_b16 v[186:187], v94 offset:0
	ds_read_b64_tr_b16 v[188:189], v94 offset:0x800
	ds_read_b64_tr_b16 v[190:191], v94 offset:0x1000
	ds_read_b64_tr_b16 v[192:193], v94 offset:0x1800
	ds_read_b64_tr_b16 v[196:197], v94 offset:0x2000
	ds_read_b64_tr_b16 v[198:199], v94 offset:0x2800
	ds_read_b64_tr_b16 v[234:235], v94 offset:0x3000
	ds_read_b64_tr_b16 v[236:237], v94 offset:0x3800
	v_permlane32_swap_b32_e32 v83, v85
	v_permlane32_swap_b32_e32 v86, v88
	v_permlane32_swap_b32_e32 v87, v89
	v_permlane32_swap_b32_e32 v90, v92
	v_permlane32_swap_b32_e32 v91, v93
	v_permlane32_swap_b32_e32 v168, v170
	v_permlane32_swap_b32_e32 v169, v171
	s_setprio 1
	s_waitcnt lgkmcnt(0)
; #define SBAR() __builtin_amdgcn_sched_barrier(0)
; template <bool FIRST>
; __device__ __forceinline__ void partialSM(f32x16& p0, f32x16& p1, float& m_reg, float& mn, float& alpha) {
;     float pmax = p0[0];
; #pragma unroll
;     for (int r = 1; r < 16; ++r) pmax = fmaxf(pmax, p0[r]);
; #pragma unroll
;     for (int r = 0; r < 16; ++r) pmax = fmaxf(pmax, p1[r]);
;     { auto rr = __builtin_amdgcn_permlane32_swap(__float_as_uint(pmax), __float_as_uint(pmax), false, false);
;       pmax = fmaxf(__uint_as_float(rr[0]), __uint_as_float(rr[1])); }
;     if (FIRST) { mn = (fabsf(pmax) <= THRL) ? 0.f : pmax; m_reg = mn; alpha = 1.f; }
;     else if (__builtin_expect(__all(pmax - m_reg <= THRL), 1)) { mn = m_reg; alpha = 1.f; }
;     else { mn = fmaxf(m_reg, pmax); alpha = __builtin_amdgcn_exp2f(m_reg - mn); m_reg = mn; }
; template <int OFF> __device__ __forceinline__ s16x4 tr_read(int vb) {
;     s16x4 r; asm volatile("ds_read_b64_tr_b16 %0, %1 offset:%2" : "=&v"(r) : "v"(vb), "i"(OFF) : "memory"); return r;
; }
; template <int D0> __device__ __forceinline__ void pv_one(f32x16& od, int vb, bf16x8 pa0, bf16x8 pa1, bf16x8 pa2, bf16x8 pa3) {
;     const s16x4 l0 = tr_read<v_rd_off(D0, 0, 0)>(vb), h0 = tr_read<v_rd_off(D0, 0, 1)>(vb), l1 = tr_read<v_rd_off(D0, 1, 0)>(vb), h1 = tr_read<v_rd_off(D0, 1, 1)>(vb);
;     const s16x4 l2 = tr_read<v_rd_off(D0, 2, 0)>(vb), h2 = tr_read<v_rd_off(D0, 2, 1)>(vb), l3 = tr_read<v_rd_off(D0, 3, 0)>(vb), h3 = tr_read<v_rd_off(D0, 3, 1)>(vb);
;     asm volatile("s_waitcnt lgkmcnt(0)" ::: "memory"); SBAR();
;     ...
;     od = __builtin_amdgcn_mfma_f32_32x32x16_bf16(pa0, PK(l0, h0), od, 0, 0, 0);
;     od = __builtin_amdgcn_mfma_f32_32x32x16_bf16(pa1, PK(l1, h1), od, 0, 0, 0);
;     od = __builtin_amdgcn_mfma_f32_32x32x16_bf16(pa2, PK(l2, h2), od, 0, 0, 0);
;     od = __builtin_amdgcn_mfma_f32_32x32x16_bf16(pa3, PK(l3, h3), od, 0, 0, 0);
;     ...
; }
; __device__ __forceinline__ void pv_d0(f32x16* o, int vb, bf16x8 pa0, bf16x8 pa1, bf16x8 pa2, bf16x8 pa3) {
;     pv_one<0>(o[0], vb, pa0, pa1, pa2, pa3); pv_one<1>(o[1], vb, pa0, pa1, pa2, pa3); pv_one<2>(o[2], vb, pa0, pa1, pa2, pa3); pv_one<3>(o[3], vb, pa0, pa1, pa2, pa3);
	s_nop 0
	v_mfma_f32_32x32x16_bf16 v[0:15], v[82:85], v[186:189], v[0:15]
	ds_read_b64_tr_b16 v[186:187], v94 offset:0x200
	ds_read_b64_tr_b16 v[188:189], v94 offset:0xa00
	v_mfma_f32_32x32x16_bf16 v[0:15], v[86:89], v[190:193], v[0:15]
	ds_read_b64_tr_b16 v[190:191], v94 offset:0x1200
	ds_read_b64_tr_b16 v[192:193], v94 offset:0x1a00
	v_mfma_f32_32x32x16_bf16 v[0:15], v[90:93], v[196:199], v[0:15]
	ds_read_b64_tr_b16 v[196:197], v94 offset:0x2200
	ds_read_b64_tr_b16 v[198:199], v94 offset:0x2a00
	v_mfma_f32_32x32x16_bf16 v[0:15], v[168:171], v[234:237], v[0:15]
	ds_read_b64_tr_b16 v[234:235], v94 offset:0x3200
	ds_read_b64_tr_b16 v[236:237], v94 offset:0x3a00
	s_waitcnt lgkmcnt(0)
	v_mfma_f32_32x32x16_bf16 v[48:63], v[82:85], v[186:189], v[48:63]
	ds_read_b64_tr_b16 v[186:187], v94 offset:0x400
	ds_read_b64_tr_b16 v[188:189], v94 offset:0xc00
	v_mfma_f32_32x32x16_bf16 v[48:63], v[86:89], v[190:193], v[48:63]
	ds_read_b64_tr_b16 v[190:191], v94 offset:0x1400
	ds_read_b64_tr_b16 v[192:193], v94 offset:0x1c00
	v_mfma_f32_32x32x16_bf16 v[48:63], v[90:93], v[196:199], v[48:63]
	ds_read_b64_tr_b16 v[196:197], v94 offset:0x2400
	ds_read_b64_tr_b16 v[198:199], v94 offset:0x2c00
	v_mfma_f32_32x32x16_bf16 v[48:63], v[168:171], v[234:237], v[48:63]
	ds_read_b64_tr_b16 v[234:235], v94 offset:0x3400
	ds_read_b64_tr_b16 v[236:237], v94 offset:0x3c00
	s_waitcnt lgkmcnt(0)
	s_setprio 0
	v_mfma_f32_32x32x16_bf16 v[32:47], v[82:85], v[186:189], v[32:47]
	ds_read_b64_tr_b16 v[186:187], v94 offset:0x600
	ds_read_b64_tr_b16 v[188:189], v94 offset:0xe00
	v_mfma_f32_32x32x16_bf16 v[32:47], v[86:89], v[190:193], v[32:47]
	ds_read_b64_tr_b16 v[190:191], v94 offset:0x1600
	ds_read_b64_tr_b16 v[192:193], v94 offset:0x1e00
	v_mfma_f32_32x32x16_bf16 v[32:47], v[90:93], v[196:199], v[32:47]
	ds_read_b64_tr_b16 v[196:197], v94 offset:0x2600
	ds_read_b64_tr_b16 v[198:199], v94 offset:0x2e00
	v_mfma_f32_32x32x16_bf16 v[32:47], v[168:171], v[234:237], v[32:47]
	ds_read_b64_tr_b16 v[234:235], v94 offset:0x3600
	ds_read_b64_tr_b16 v[236:237], v94 offset:0x3e00
	s_waitcnt lgkmcnt(0)
	v_mfma_f32_32x32x16_bf16 v[16:31], v[82:85], v[186:189], v[16:31]
	v_max_f32_e32 v82, v97, v97
	v_max_f32_e32 v83, v96, v96
	v_max_f32_e32 v82, v83, v82
	v_max3_f32 v82, v82, v98, v99
	v_max3_f32 v82, v82, v100, v101
	v_max3_f32 v82, v82, v102, v103
	v_max3_f32 v82, v82, v104, v105
	v_mfma_f32_32x32x16_bf16 v[16:31], v[86:89], v[190:193], v[16:31]
	v_max3_f32 v82, v82, v106, v107
	v_max3_f32 v82, v82, v108, v109
	v_max3_f32 v82, v82, v110, v111
	v_max3_f32 v82, v82, v64, v65
	v_max3_f32 v82, v82, v66, v67
	v_max3_f32 v82, v82, v68, v69
	v_max3_f32 v82, v82, v70, v71
	v_mfma_f32_32x32x16_bf16 v[16:31], v[90:93], v[196:199], v[16:31]
	v_max3_f32 v82, v82, v72, v73
	v_max3_f32 v82, v82, v74, v75
	v_max3_f32 v82, v82, v76, v77
	v_max3_f32 v82, v82, v78, v79
	v_mov_b32_e32 v83, v82
	s_nop 1
	v_permlane32_swap_b32_e32 v82, v83
	v_max_f32_e32 v83, v83, v83
	v_max_f32_e32 v82, v82, v82
	v_mfma_f32_32x32x16_bf16 v[16:31], v[168:171], v[234:237], v[16:31]
	v_max_f32_e32 v82, v82, v83
	v_sub_f32_e32 v83, v82, v184
	s_mov_b32 s0, 0x41300000
	v_cmp_ge_f32_e32 vcc, s0, v83
	v_mov_b32_e32 v182, v184
	s_cmp_eq_u64 vcc, exec
	s_cbranch_scc0 .Latt_slow2
	s_cmp_lg_u32 s19, 0
	s_cbranch_scc0 .LBB0_229
	v_mov_b32_e32 v184, 1.0
